# F1: RMS partial-sum load for a new row panel issued before the K-loop into v240-243 instead of in the epilogue; on top of v37
# speedup vs baseline: 1.0010x; 1.0010x over previous
.LBB0_569:
	s_cmp_eq_u32 s42, s36
	s_cbranch_scc1 .Lrs_pref_skip
	s_mov_b64 vcc, exec
	s_and_b64 exec, exec, s[2:3]
	v_lshl_add_u32 v240, s42, 8, v144
	v_ashrrev_i32_e32 v241, 31, v240
	v_lshl_add_u64 v[240:241], v[240:241], 4, s[46:47]
	global_load_dwordx4 v[240:243], v[240:241], off
	s_mov_b64 exec, vcc

.LBB0_573:
	s_cmp_eq_u32 s42, s36
	s_cbranch_scc1 .LBB0_577
	s_barrier
	s_and_saveexec_b64 s[18:19], s[2:3]
	s_cbranch_execz .LBB0_576
	s_waitcnt vmcnt(0) lgkmcnt(0)
	v_mov_b32_e32 v148, v240
	v_mov_b32_e32 v149, v241
	v_mov_b32_e32 v150, v242
	v_mov_b32_e32 v151, v243
	v_mov_b32_e32 v140, v149
	v_mov_b32_e32 v141, v150
	v_mov_b32_e32 v149, v151
	v_pk_add_f32 v[140:141], v[140:141], v[148:149]
	s_nop 0
	v_add_f32_e32 v140, v140, v141
	v_fmamk_f32 v140, v140, 0x3a800000, v205
	v_mul_f32_e32 v141, 0x4b800000, v140
	v_cmp_gt_f32_e32 vcc, s67, v140
	s_nop 1
	v_cndmask_b32_e32 v140, v140, v141, vcc
	v_rsq_f32_e32 v140, v140
	s_nop 0
	v_mul_f32_e32 v141, 0x45800000, v140
	v_cndmask_b32_e32 v140, v140, v141, vcc
	ds_write_b32 v145, v140
